# out-projection GEMM: removed the full VMEM drain before re-entering the K-loop after the final epilogue
# speedup vs baseline: 1.0082x; 1.0059x over previous
; template <class Epi, class Sched>
; __device__ __forceinline__ void gemm_phase(const int TID, LAS unsigned char* lds, const int lda, const int ldb, const Sched& S, const Epi& E) {
;     ...
;         if (!has_next) break;
; #pragma unroll
;         for (int a = 0; a < 2; ++a)
; #pragma unroll
;             for (int b = 0; b < 2; ++b)
; #pragma unroll
;                 for (int m = 0; m < 4; ++m)
; #pragma unroll
;                     for (int n = 0; n < 2; ++n) acc[a][b][m][n] = (f32x4){0.f, 0.f, 0.f, 0.f};
;         cur = nxt; cA = nA; cB = nB; ++ui;
.LBB0_235:
	s_add_i32 s45, s68, -2
	s_add_u32 s47, s54, 0x100
	s_addc_u32 s69, s55, 0
	s_add_u32 s52, s52, 0x80080
	s_addc_u32 s53, s53, 0
	s_mov_b32 s54, 0
	s_cmp_lg_u32 s41, 0
	s_cbranch_scc1 .Lk6_nozero
	v_mov_b32_e32 v0, 0
	v_mov_b32_e32 v1, v0
	v_mov_b32_e32 v2, v0
	v_mov_b32_e32 v3, v0
	v_mov_b32_e32 v4, v0
	v_mov_b32_e32 v5, v0
	v_mov_b32_e32 v6, v0
	v_mov_b32_e32 v7, v0
	v_mov_b32_e32 v22, v0
	v_mov_b32_e32 v23, v0
	v_mov_b32_e32 v24, v0
	v_mov_b32_e32 v25, v0
	v_mov_b32_e32 v26, v0
	v_mov_b32_e32 v27, v0
	v_mov_b32_e32 v28, v0
	v_mov_b32_e32 v29, v0
	v_mov_b32_e32 v38, v0
	v_mov_b32_e32 v39, v0
	v_mov_b32_e32 v40, v0
	v_mov_b32_e32 v41, v0
	v_mov_b32_e32 v42, v0
	v_mov_b32_e32 v43, v0
	v_mov_b32_e32 v44, v0
	v_mov_b32_e32 v45, v0
	v_mov_b32_e32 v54, v0
	v_mov_b32_e32 v55, v0
	v_mov_b32_e32 v56, v0
	v_mov_b32_e32 v57, v0
	v_mov_b32_e32 v58, v0
	v_mov_b32_e32 v59, v0
	v_mov_b32_e32 v60, v0
	v_mov_b32_e32 v61, v0
	v_mov_b32_e32 v8, v0
	v_mov_b32_e32 v9, v0
	v_mov_b32_e32 v10, v0
	v_mov_b32_e32 v11, v0
	v_mov_b32_e32 v18, v0
	v_mov_b32_e32 v19, v0
	v_mov_b32_e32 v20, v0
	v_mov_b32_e32 v21, v0
	v_mov_b32_e32 v30, v0
	v_mov_b32_e32 v31, v0
	v_mov_b32_e32 v32, v0
	v_mov_b32_e32 v33, v0
	v_mov_b32_e32 v34, v0
	v_mov_b32_e32 v35, v0
	v_mov_b32_e32 v36, v0
	v_mov_b32_e32 v37, v0
	v_mov_b32_e32 v46, v0
	v_mov_b32_e32 v47, v0
	v_mov_b32_e32 v48, v0
	v_mov_b32_e32 v49, v0
	v_mov_b32_e32 v50, v0
	v_mov_b32_e32 v51, v0
	v_mov_b32_e32 v52, v0
	v_mov_b32_e32 v53, v0
	v_mov_b32_e32 v62, v0
	v_mov_b32_e32 v63, v0
	v_mov_b32_e32 v64, v0
	v_mov_b32_e32 v65, v0
	v_mov_b32_e32 v66, v0
	v_mov_b32_e32 v67, v0
	v_mov_b32_e32 v68, v0
	v_mov_b32_e32 v69, v0
	s_waitcnt lgkmcnt(0)
	v_mov_b32_e32 v70, v0
	v_mov_b32_e32 v71, v0
	v_mov_b32_e32 v72, v0
	v_mov_b32_e32 v73, v0
	v_mov_b32_e32 v74, v0
	v_mov_b32_e32 v75, v0
	v_mov_b32_e32 v76, v0
	v_mov_b32_e32 v77, v0
	v_mov_b32_e32 v86, v0
	v_mov_b32_e32 v87, v0
	v_mov_b32_e32 v88, v0
	v_mov_b32_e32 v89, v0
	v_mov_b32_e32 v90, v0
	v_mov_b32_e32 v91, v0
	v_mov_b32_e32 v92, v0
	v_mov_b32_e32 v93, v0
	v_mov_b32_e32 v102, v0
	v_mov_b32_e32 v103, v0
	v_mov_b32_e32 v104, v0
	v_mov_b32_e32 v105, v0
	v_mov_b32_e32 v110, v0
	v_mov_b32_e32 v111, v0
	v_mov_b32_e32 v112, v0
	v_mov_b32_e32 v113, v0
	v_mov_b32_e32 v126, v0
	v_mov_b32_e32 v127, v0
	v_mov_b32_e32 v128, v0
	v_mov_b32_e32 v129, v0
	v_mov_b32_e32 v130, v0
	v_mov_b32_e32 v131, v0
	v_mov_b32_e32 v132, v0
	v_mov_b32_e32 v133, v0
	v_mov_b32_e32 v78, v0
	v_mov_b32_e32 v79, v0
	v_mov_b32_e32 v80, v0
	v_mov_b32_e32 v81, v0
	v_mov_b32_e32 v82, v0
	v_mov_b32_e32 v83, v0
	v_mov_b32_e32 v84, v0
	v_mov_b32_e32 v85, v0
	v_mov_b32_e32 v94, v0
	v_mov_b32_e32 v95, v0
	v_mov_b32_e32 v96, v0
	v_mov_b32_e32 v97, v0
	v_mov_b32_e32 v98, v0
	v_mov_b32_e32 v99, v0
	v_mov_b32_e32 v100, v0
	v_mov_b32_e32 v101, v0
	v_mov_b32_e32 v114, v0
	v_mov_b32_e32 v115, v0
	v_mov_b32_e32 v116, v0
	v_mov_b32_e32 v117, v0
	v_mov_b32_e32 v122, v0
	v_mov_b32_e32 v123, v0
	v_mov_b32_e32 v124, v0
	v_mov_b32_e32 v125, v0
	v_mov_b32_e32 v138, v0
	v_mov_b32_e32 v139, v0
	v_mov_b32_e32 v140, v0
	v_mov_b32_e32 v141, v0
	v_mov_b32_e32 v142, v0
	v_mov_b32_e32 v143, v0
	v_mov_b32_e32 v144, v0
	v_mov_b32_e32 v145, v0
